# V4 = V3 + prep phase: odd workgroups run x-normalisation before weight conversion (overlap bandwidth-bound and latency-bound passes)
# baseline (speedup 1.0000x reference)
; #define LAS __attribute__((address_space(3)))
; __global__ void __launch_bounds__(NTHREADS, 2) fwd_kernel(Args a) {
;     extern __shared__ __attribute__((aligned(16))) unsigned char lds_raw[];
;     LAS unsigned char* lds = (LAS unsigned char*)lds_raw;
;     const int G = gridDim.x, bx = blockIdx.x, vcu = (G % 8 == 0) ? (bx % 8) * (G / 8) + bx / 8 : bx;
_Z10fwd_kernel4Args:
	s_mov_b32 s98, 0
	s_load_dword s66, s[0:1], 0xd8
	s_mov_b64 s[90:91], s[0:1]
	s_mov_b32 s33, s2
	s_mov_b32 s58, s2
	s_waitcnt lgkmcnt(0)
	s_and_b32 s0, s66, 7
	s_cmp_lg_u32 s0, 0
	s_cbranch_scc1 .LBB0_2
	s_ashr_i32 s1, s33, 31
	s_lshr_b32 s1, s1, 29
	s_add_i32 s1, s33, s1
	s_and_b32 s2, s1, -8
	s_ashr_i32 s0, s66, 3
	s_sub_i32 s2, s33, s2
	s_mul_i32 s0, s0, s2
	s_ashr_i32 s1, s1, 3
	s_add_i32 s58, s0, s1

; #define LAS __attribute__((address_space(3)))
; __device__ __forceinline__ void prep_phase(const Args& a, LAS unsigned char* lds, int vcu, int G, int wave, int lane) {
;     unsigned char* ws = a.ws;
;     LAS float* scr = (LAS float*)(lds + wave * 16384);
;     const int gw = vcu * NWAVES + wave, NGW = G * NWAVES;
;     constexpr int I_UP = (DM / 64) * (NUP / 32), I_DN = (DFF / 64) * (DM / 32), I_IN = (DM / 64) * (NIN / 32), I_O = (512 / 64) * (DM / 32), I_OUT = (DM / 64) * (DM / 32), I_C1 = (2048 / 64) * (128 / 32), I_C2 = (128 / 64) * (64 / 32);
;     constexpr int NITEMS = 2 * I_UP + 2 * I_DN + I_IN + 2 * I_O + I_OUT + 2 * I_C1 + 2 * I_C2;
;     for (int it = gw; it < NITEMS; it += NGW) {
.Lprep_entry:
	v_mbcnt_hi_u32_b32 v69, -1, v230
	v_readlane_b32 s0, v248, 0
	s_lshl_b32 s37, s58, 3
	s_lshl_b32 s59, s66, 3
	v_add_u32_e32 v1, s0, v69
	s_load_dwordx2 s[38:39], s[90:91], 0xc8
	v_readfirstlane_b32 s60, v1
	s_ashr_i32 s0, s60, 6
	v_and_b32_e32 v68, 63, v1
	s_add_i32 s36, s0, s37
	s_mov_b32 s45, 0
	s_mov_b64 s[46:47], s[90:91]
	s_cmpk_gt_i32 s36, 0x3007
	v_lshlrev_b32_e32 v0, 3, v68
	s_cbranch_scc1 .LBB0_293
	s_cmp_lg_u32 s98, 0
	s_cbranch_scc1 .Lprep_w
	s_bitcmp1_b32 s33, 0
	s_cbranch_scc0 .Lprep_w
	s_mov_b32 s98, 1
	s_branch .LBB0_293
.Lprep_w:
	v_and_b32_e32 v3, 56, v0
	s_lshl_b32 s0, s0, 14
	v_lshlrev_b32_e32 v4, 1, v3
	v_mov_b32_e32 v5, 0
	s_add_i32 s2, s0, 0
	v_lshrrev_b32_e32 v52, 3, v68
	s_waitcnt lgkmcnt(0)
	v_lshl_add_u64 v[28:29], s[38:39], 0, v[4:5]
	s_mov_b64 s[0:1], 0x3210000
	v_lshrrev_b32_e32 v2, 5, v68
	v_mul_u32_u24_e32 v8, 0x84, v3
	v_lshl_add_u64 v[6:7], v[28:29], 0, s[0:1]
	v_lshlrev_b32_e32 v3, 2, v52
	s_mov_b64 s[0:1], 0x3200000
	s_movk_i32 s3, 0x84
	v_add3_u32 v53, s2, v8, v3
	v_lshl_add_u64 v[8:9], v[28:29], 0, s[0:1]
	s_mov_b64 s[0:1], 0x3180000
	v_or_b32_e32 v3, 2, v2
	v_mov_b32_e32 v4, 0x108
	v_lshl_add_u64 v[10:11], v[28:29], 0, s[0:1]
	s_mov_b64 s[0:1], 0x3100000
	v_mad_u32_u24 v58, v3, s3, v4
	v_mov_b32_e32 v4, 0x318
	v_lshl_add_u64 v[12:13], v[28:29], 0, s[0:1]
	s_mov_b64 s[0:1], 0x1e00000
	v_mad_u32_u24 v59, v3, s3, v4
	v_mov_b32_e32 v4, 0x528
	v_lshl_add_u64 v[14:15], v[28:29], 0, s[0:1]
	s_mov_b64 s[0:1], 0x1c00400
	v_mad_u32_u24 v60, v3, s3, v4
	v_mov_b32_e32 v4, 0x738
	v_lshl_add_u64 v[16:17], v[28:29], 0, s[0:1]
	s_mov_b64 s[0:1], 0x1c00000
	v_mad_u32_u24 v61, v3, s3, v4
	v_mov_b32_e32 v4, 0x948
	v_lshl_add_u64 v[18:19], v[28:29], 0, s[0:1]
	v_mad_u32_u24 v62, v3, s3, v4
	v_mov_b32_e32 v4, 0xb58
	s_mov_b64 s[0:1], 0x1200000
	s_load_dwordx8 s[20:27], s[46:47], 0x8
	s_load_dwordx16 s[4:19], s[46:47], 0x68
	v_mad_u32_u24 v63, v3, s3, v4
	v_mov_b32_e32 v4, 0xd68
	v_lshl_add_u64 v[20:21], v[28:29], 0, s[0:1]
	s_mov_b64 s[0:1], 0x2b00000
	v_mad_u32_u24 v64, v3, s3, v4
	v_mov_b32_e32 v4, 0xf78
	v_lshl_add_u64 v[22:23], v[28:29], 0, s[0:1]
	s_mov_b64 s[0:1], 0xc00000
	v_mad_u32_u24 v65, v3, s3, v4
	v_mov_b32_e32 v4, 0x1188
	v_lshl_add_u64 v[24:25], v[28:29], 0, s[0:1]
	s_mov_b64 s[0:1], 0x2000000
	s_load_dwordx2 s[52:53], s[46:47], 0x28
	s_load_dwordx4 s[28:31], s[46:47], 0xa8
	v_and_b32_e32 v1, 31, v1
	v_mad_u32_u24 v66, v3, s3, v4
	v_mov_b32_e32 v4, 0x1398
	v_lshl_add_u64 v[26:27], v[28:29], 0, s[0:1]
	s_mov_b64 s[0:1], 0x100000
	s_waitcnt lgkmcnt(0)
	s_cmp_lg_u64 s[26:27], 0
	v_lshl_add_u32 v50, v1, 2, s2
	v_mad_u32_u24 v67, v3, s3, v4
	v_mov_b32_e32 v4, 0x15a8
	v_lshl_add_u64 v[28:29], v[28:29], 0, s[0:1]
	s_cselect_b64 s[0:1], -1, 0
	s_cmp_lg_u64 s[18:19], 0
	v_mad_u32_u24 v51, v2, s3, v50
	v_mad_u32_u24 v70, v3, s3, v4
	v_mov_b32_e32 v4, 0x17b8
	s_cselect_b64 s[48:49], -1, 0
	s_cmp_lg_u64 s[20:21], 0
	v_or_b32_e32 v54, 8, v52
	v_or_b32_e32 v55, 16, v52
	v_or_b32_e32 v56, 24, v52
	v_mul_u32_u24_e32 v57, 0x84, v3
	v_mad_u32_u24 v71, v3, s3, v4
	v_writelane_b32 v248, s0, 1
	s_cselect_b64 s[50:51], -1, 0
	v_mov_b32_e32 v3, v5
	s_lshl_b32 s61, s36, 5
	s_lshl_b32 s62, s59, 5
	s_lshl_b32 s63, s36, 4
	s_lshl_b32 s64, s59, 4
	s_lshl_b32 s65, s36, 1
	s_lshl_b32 s68, s59, 1
	s_movk_i32 s69, 0x1320
	s_mov_b32 s67, 0x42f00
	v_add_u32_e32 v72, 0x400, v51
	v_add_u32_e32 v73, 0x800, v51
	v_add_u32_e32 v74, 0xc00, v51
	v_add_u32_e32 v75, 0x1000, v51
	v_add_u32_e32 v76, 0x1400, v51
	v_add_u32_e32 v77, 0x1800, v51
	v_mov_b32_e32 v78, 0x800
	s_movk_i32 s74, 0x5800
	s_mov_b32 s75, 0xb000
	s_mov_b32 s76, 0x21000
	s_mov_b32 s77, 0x37000
	s_mov_b32 s78, 0x42000
	s_mov_b32 s79, 0x4d000
	s_mov_b32 s80, 0x58000
	s_mov_b32 s81, 0x63000
	s_mov_b32 s82, 0x6e000
	s_mov_b32 s83, 0x79000
	s_mov_b32 s84, 0x84000
	s_mov_b32 s85, 0x8f000
	s_mov_b32 s86, 0x9a000
	s_mov_b32 s87, 0xa5000
	s_mov_b32 s88, 0xb0000
	s_mov_b32 s89, 0xbb000
	s_mov_b32 s90, 0xc6000
	s_mov_b32 s91, 0xd1000
	s_mov_b32 s92, 0xdc000
	s_mov_b32 s93, 0xe7000
	s_mov_b32 s94, 0xf2000
	s_mov_b32 s95, 0xfd000
	s_mov_b32 s96, 0x108000
	s_mov_b32 s97, 0x113000
	s_mov_b32 s70, 0x11e000
	s_mov_b32 s71, 0x129000
	s_mov_b32 s72, 0x134000
	s_mov_b32 s73, s36
	v_writelane_b32 v248, s1, 2
	s_branch .LBB0_12

; __device__ __forceinline__ void prep_phase(const Args& a, LAS unsigned char* lds, int vcu, int G, int wave, int lane) {
;     ...
;     const float* x = a.in[0]; bf16_t* XB = (bf16_t*)(ws + WS_XB);
;     for (int m = gw; m < MTOK; m += 4 * NGW) {
;         f32x4 v[4][4]; float s[4];
; #pragma unroll
;         for (int r = 0; r < 4; ++r) { const int mr = m + r * NGW; const f32x4* xr = (const f32x4*)(x + (size_t)(mr < MTOK ? mr : m) * DM) + lane;
; #pragma unroll
;             for (int j = 0; j < 4; ++j) v[r][j] = xr[64 * j]; }
; #pragma unroll
.LBB0_293:
	v_and_b32_e32 v76, 64, v69
	v_xor_b32_e32 v75, 1, v69
	v_xor_b32_e32 v74, 2, v69
	v_xor_b32_e32 v73, 4, v69
	v_xor_b32_e32 v72, 8, v69
	v_xor_b32_e32 v71, 16, v69
	v_xor_b32_e32 v70, 32, v69
	s_mov_b64 s[90:91], s[46:47]
	s_cmp_eq_u32 s98, 2
	s_cbranch_scc1 .LBB0_302
	s_cmpk_gt_i32 s36, 0x7fff
	s_cbranch_scc1 .LBB0_302
	s_load_dwordx2 s[0:1], s[90:91], 0x0
	v_add_u32_e32 v1, 64, v76
	v_lshlrev_b32_e32 v2, 4, v68
	v_mov_b32_e32 v3, 0
	v_cmp_lt_i32_e32 vcc, v75, v1
	s_waitcnt lgkmcnt(0)
	v_lshl_add_u64 v[64:65], s[0:1], 0, v[2:3]
	s_mov_b64 s[0:1], 0x3a00000
	v_cndmask_b32_e32 v2, v69, v75, vcc
	v_cmp_lt_i32_e32 vcc, v74, v1
	v_lshlrev_b32_e32 v77, 2, v2
	v_mov_b32_e32 v83, 0x358637bd
	v_cndmask_b32_e32 v2, v69, v74, vcc
	v_cmp_lt_i32_e32 vcc, v73, v1
	v_lshlrev_b32_e32 v78, 2, v2
	s_mov_b32 s12, s36
	v_cndmask_b32_e32 v2, v69, v73, vcc
	v_cmp_lt_i32_e32 vcc, v72, v1
	v_lshlrev_b32_e32 v79, 2, v2
	s_nop 0
	v_cndmask_b32_e32 v2, v69, v72, vcc
	v_cmp_lt_i32_e32 vcc, v71, v1
	v_lshlrev_b32_e32 v80, 2, v2
	s_nop 0
	v_cndmask_b32_e32 v2, v69, v71, vcc
	v_cmp_lt_i32_e32 vcc, v70, v1
	v_lshlrev_b32_e32 v81, 2, v2
	s_nop 0
	v_cndmask_b32_e32 v1, v69, v70, vcc
	v_lshlrev_b32_e32 v82, 2, v1
	v_mov_b32_e32 v1, v3
	v_lshl_add_u64 v[0:1], s[38:39], 0, v[0:1]
	v_lshl_add_u64 v[66:67], v[0:1], 0, s[0:1]
	s_lshl_b32 s0, s66, 4
	s_mul_i32 s1, s66, 24
	s_branch .LBB0_296

; __device__ __forceinline__ unsigned cvt_pk_bf16(float lo, float hi) { f32x2 v = {lo, hi}; bf16x2_t b = __builtin_convertvector(v, bf16x2_t); return __builtin_bit_cast(unsigned, b); }
; __device__ __forceinline__ void prep_phase(const Args& a, LAS unsigned char* lds, int vcu, int G, int wave, int lane) {
;     ...
;     const float* x = a.in[0]; bf16_t* XB = (bf16_t*)(ws + WS_XB);
;     for (int m = gw; m < MTOK; m += 4 * NGW) {
;         f32x4 v[4][4]; float s[4];
; #pragma unroll
;         for (int r = 0; r < 4; ++r) { const int mr = m + r * NGW; const f32x4* xr = (const f32x4*)(x + (size_t)(mr < MTOK ? mr : m) * DM) + lane;
; #pragma unroll
;             for (int j = 0; j < 4; ++j) v[r][j] = xr[64 * j]; }
; #pragma unroll
;         for (int r = 0; r < 4; ++r) { float t = 0.f;
; #pragma unroll
;             for (int j = 0; j < 4; ++j) t += (v[r][j][0] * v[r][j][0] + v[r][j][1] * v[r][j][1]) + (v[r][j][2] * v[r][j][2] + v[r][j][3] * v[r][j][3]);
;             s[r] = wave_sum(t); }
; #pragma unroll
;         for (int r = 0; r < 4; ++r) { const int mr = m + r * NGW;
;             const float ri = __builtin_amdgcn_rsqf(s[r] * (1.0f / 1024.0f) + RMS_EPS);
;             if (mr < MTOK) { u32x2* o8 = (u32x2*)(XB + (size_t)mr * DM) + lane;
; #pragma unroll
;                 for (int j = 0; j < 4; ++j) { u32x2 w; w.x = cvt_pk_bf16(v[r][j][0] * ri, v[r][j][1] * ri); w.y = cvt_pk_bf16(v[r][j][2] * ri, v[r][j][3] * ri); o8[64 * j] = w; } } }
;     }
;     { float* TAB = (float*)(ws + WS_TAB); const float* tbl = a.in[23];
;       for (int i = gw * 64 + lane; i < 8 * 128; i += NGW * 64) { const int h = i >> 7, d = i & 127; TAB[i] = tbl[(int)T5_BUCKET[d] * 8 + h] * LOG2E; } }
.LBB0_302:
	s_cmp_eq_u32 s98, 1
	s_cbranch_scc0 .Lprep_cont
	s_mov_b32 s98, 2
	s_branch .Lprep_entry
